# lever 9 loop-edge edit: cross-attn tile loop back edge rotated to a single taken branch (s_mov before conditional back-branch)
# speedup vs baseline: 1.0042x; 1.0042x over previous
; __device__ __forceinline__ unsigned cvt_pk_bf16(float lo, float hi) { unsigned r; asm volatile("v_cvt_pk_bf16_f32 %0, %1, %2" : "=v"(r) : "v"(lo), "v"(hi)); return r; }
; template <int D, int DV, int MODE, int NMAP, int KT> ...
;     ...
;                     const float nm = -m[mp]; float ps = 0.f;
; #pragma unroll
;                     for (int nb = 0; nb < NB; ++nb)
; #pragma unroll
;                         for (int j = 0; j < 4; ++j) { const float p = __builtin_amdgcn_exp2f(fmaf(s[nb][j], sc, nm)); ps += p; s[nb][j] = p; }
;                     l[mp] += ps;
;                 } else {
;                     const float rowf = __builtin_amdgcn_exp2f(l2g * (float)(myrow - kt * KT));
; #pragma unroll
;                     for (int nb = 0; nb < NB; ++nb)
; #pragma unroll
;                         for (int j = 0; j < 4; ++j) { float p = s[nb][j] * (rowf * ck[nb][j]); if (diag && (kt * KT + nb * 16 + g4 * 4 + j > myrow)) p = 0.f; s[nb][j] = p; }
;                 }
; #pragma unroll
;                 for (int kk = 0; kk < KK2; ++kk) { u32x4 wv; wv.x = cvt_pk_bf16(s[2 * kk][0], s[2 * kk][1]); wv.y = cvt_pk_bf16(s[2 * kk][2], s[2 * kk][3]);
;                     wv.z = cvt_pk_bf16(s[2 * kk + 1][0], s[2 * kk + 1][1]); wv.w = cvt_pk_bf16(s[2 * kk + 1][2], s[2 * kk + 1][3]); pb[mp][kk] = __builtin_bit_cast(bf16x8, wv); }
;             }
;             {
;                 constexpr int CBB = 4, NCB = (DV / 16) / CBB, NVB = KK2 * NCB;
;                 bf16x8 vfr[2][CBB];
;     ...
;                 AT_VLOAD(0, 0);
; #pragma unroll
;                 for (int b_ = 0; b_ < NVB; ++b_) {
;                     if (b_ + 1 < NVB) AT_VLOAD(b_ + 1, (b_ + 1) & 1);
;                     __builtin_amdgcn_sched_barrier(0);
;                     const int kk_ = b_ / NCB, c0_ = (b_ % NCB) * CBB;
;                     __builtin_amdgcn_s_setprio(1);
; #pragma unroll
;                     for (int x_ = 0; x_ < CBB; ++x_)
; #pragma unroll
;                         for (int mp = 0; mp < NMAP; ++mp) o[mp][c0_ + x_] = __builtin_amdgcn_mfma_f32_16x16x32_bf16(vfr[b_ & 1][x_], pb[mp][kk_], o[mp][c0_ + x_], 0, 0, 0);
.LBB0_605:
	v_fma_f32 v142, v142, s0, -v175
	v_exp_f32_e32 v142, v142
	v_fma_f32 v143, v143, s0, -v175
	v_exp_f32_e32 v143, v143
	v_fma_f32 v144, v144, s0, -v175
	v_exp_f32_e32 v144, v144
	v_fma_f32 v145, v145, s0, -v175
	v_exp_f32_e32 v145, v145
	v_fma_f32 v138, v138, s0, -v175
	v_add_f32_e32 v176, 0, v142
	v_exp_f32_e32 v138, v138
	v_fma_f32 v139, v139, s0, -v175
	v_add_f32_e32 v176, v143, v176
	v_exp_f32_e32 v139, v139
	v_fma_f32 v140, v140, s0, -v175
	v_add_f32_e32 v176, v144, v176
	v_exp_f32_e32 v140, v140
	v_fma_f32 v141, v141, s0, -v175
	v_add_f32_e32 v176, v145, v176
	v_exp_f32_e32 v141, v141
	v_fma_f32 v134, v134, s0, -v175
	v_add_f32_e32 v176, v138, v176
	v_exp_f32_e32 v177, v134
	v_add_f32_e32 v176, v139, v176
	v_add_f32_e32 v176, v140, v176
	v_add_f32_e32 v176, v141, v176
	v_fma_f32 v135, v135, s0, -v175
	v_add_f32_e32 v134, v177, v176
	v_exp_f32_e32 v176, v135
	v_fma_f32 v135, v136, s0, -v175
	v_exp_f32_e32 v178, v135
	v_fma_f32 v135, v137, s0, -v175
	v_exp_f32_e32 v179, v135
	v_fma_f32 v130, v130, s0, -v175
	v_exp_f32_e32 v180, v130
	v_fma_f32 v131, v131, s0, -v175
	v_add_f32_e32 v134, v176, v134
	v_exp_f32_e32 v181, v131
	v_fma_f32 v131, v132, s0, -v175
	v_add_f32_e32 v134, v178, v134
	v_exp_f32_e32 v182, v131
	v_fma_f32 v131, v133, s0, -v175
	v_add_f32_e32 v134, v179, v134
	v_exp_f32_e32 v133, v131
	v_add_f32_e32 v130, v180, v134
	v_add_f32_e32 v130, v181, v130
	v_add_f32_e32 v130, v182, v130
	v_add3_u32 v184, s15, v158, v149
	v_add_f32_e32 v130, v133, v130
	v_add_u32_e32 v210, 0x8000, v184
	v_add_u32_e32 v212, 0x8800, v184
	v_add_u32_e32 v213, 0x9000, v184
	v_add_u32_e32 v214, 0x9800, v184
	v_add_u32_e32 v215, 0xa800, v184
	v_add_u32_e32 v216, 0xb000, v184
	v_add_u32_e32 v217, 0xb800, v184
	v_add_u32_e32 v226, 0xc000, v184
	v_add_f32_e32 v159, v159, v130
	v_cvt_pk_bf16_f32 v134, v142, v143
	v_cvt_pk_bf16_f32 v135, v144, v145
	v_cvt_pk_bf16_f32 v136, v138, v139
	v_cvt_pk_bf16_f32 v137, v140, v141
	v_cvt_pk_bf16_f32 v130, v177, v176
	v_cvt_pk_bf16_f32 v131, v178, v179
	v_cvt_pk_bf16_f32 v132, v180, v181
	v_cvt_pk_bf16_f32 v133, v182, v133
	ds_read_b64 v[138:139], v210 offset:1024
	ds_read_b64 v[140:141], v210 offset:1056
	ds_read_b64 v[142:143], v212 offset:1280
	ds_read_b64 v[144:145], v212 offset:1312
	ds_read_b64 v[176:177], v213 offset:1536
	ds_read_b64 v[178:179], v213 offset:1568
	ds_read_b64 v[180:181], v214 offset:1792
	ds_read_b64 v[182:183], v214 offset:1824
	ds_read_b64 v[194:195], v215
	ds_read_b64 v[196:197], v215 offset:32
	ds_read_b64 v[198:199], v216 offset:256
	ds_read_b64 v[200:201], v216 offset:288
	ds_read_b64 v[202:203], v217 offset:512
	ds_read_b64 v[204:205], v217 offset:544
	ds_read_b64 v[206:207], v226 offset:768
	ds_read_b64 v[208:209], v226 offset:800
	v_add_u32_e32 v185, 0x8400, v184
	s_setprio 1
	s_waitcnt lgkmcnt(14)
	v_mfma_f32_16x16x32_bf16 v[62:65], v[138:141], v[134:137], v[62:65]
	s_waitcnt lgkmcnt(12)
	v_mfma_f32_16x16x32_bf16 v[58:61], v[142:145], v[134:137], v[58:61]
	s_waitcnt lgkmcnt(10)
	v_mfma_f32_16x16x32_bf16 v[54:57], v[176:179], v[134:137], v[54:57]
	s_waitcnt lgkmcnt(8)
	v_mfma_f32_16x16x32_bf16 v[50:53], v[180:183], v[134:137], v[50:53]
	s_setprio 0
	v_add_u32_e32 v227, 0xc800, v184
	v_add_u32_e32 v228, 0xd000, v184
	v_add_u32_e32 v229, 0xd800, v184
	v_add_u32_e32 v230, 0xe000, v184
	ds_read_b64 v[138:139], v227 offset:1024
	ds_read_b64 v[140:141], v227 offset:1056
	ds_read_b64 v[142:143], v228 offset:1280
	ds_read_b64 v[144:145], v228 offset:1312
	ds_read_b64 v[176:177], v229 offset:1536
	ds_read_b64 v[178:179], v229 offset:1568
	ds_read_b64 v[180:181], v230 offset:1792
	ds_read_b64 v[182:183], v230 offset:1824
	s_setprio 1
	s_waitcnt lgkmcnt(14)
	v_mfma_f32_16x16x32_bf16 v[46:49], v[194:197], v[134:137], v[46:49]
	s_waitcnt lgkmcnt(12)
	v_mfma_f32_16x16x32_bf16 v[42:45], v[198:201], v[134:137], v[42:45]
	s_waitcnt lgkmcnt(10)
	v_mfma_f32_16x16x32_bf16 v[38:41], v[202:205], v[134:137], v[38:41]
	s_waitcnt lgkmcnt(8)
	v_mfma_f32_16x16x32_bf16 v[34:37], v[206:209], v[134:137], v[34:37]
	s_setprio 0
	v_add_u32_e32 v231, 0xf000, v184
	v_add_u32_e32 v232, 0xf800, v184
	v_add_u32_e32 v202, 0x7800, v185
	v_add_u32_e32 v185, 0x8000, v185
	ds_read_b64 v[194:195], v231
	ds_read_b64 v[196:197], v231 offset:32
	ds_read_b64 v[198:199], v232 offset:256
	ds_read_b64 v[200:201], v232 offset:288
	ds_read_b64 v[204:205], v202 offset:1568
	ds_read_b64 v[202:203], v202 offset:1536
	ds_read_b64 v[206:207], v185 offset:1792
	ds_read_b64 v[208:209], v185 offset:1824
	s_setprio 1
	s_waitcnt lgkmcnt(14)
; template <int D, int DV, int MODE, int NMAP, int KT> ...
;     ...
;     for (int kt = 0; kt < nkt; ++kt) {
;         __syncthreads();
;         const int cur = (kt & 1) * BUF_BYTES;
;         if (kt + 1 < nkt) { AT_STORE(((kt + 1) & 1) * BUF_BYTES); if (kt + 2 < nkt) AT_LOAD(kt + 2); }
;     ...
;                 for (int b_ = 0; b_ < NVB; ++b_) {
;                     if (b_ + 1 < NVB) AT_VLOAD(b_ + 1, (b_ + 1) & 1);
;                     __builtin_amdgcn_sched_barrier(0);
;                     const int kk_ = b_ / NCB, c0_ = (b_ % NCB) * CBB;
;                     __builtin_amdgcn_s_setprio(1);
; #pragma unroll
;                     for (int x_ = 0; x_ < CBB; ++x_)
; #pragma unroll
;                         for (int mp = 0; mp < NMAP; ++mp) o[mp][c0_ + x_] = __builtin_amdgcn_mfma_f32_16x16x32_bf16(vfr[b_ & 1][x_], pb[mp][kk_], o[mp][c0_ + x_], 0, 0, 0);
;                     __builtin_amdgcn_s_setprio(0);
;                     __builtin_amdgcn_sched_barrier(0);
;                 }
	v_mfma_f32_16x16x32_bf16 v[30:33], v[138:141], v[134:137], v[30:33]
	s_waitcnt lgkmcnt(12)
	v_mfma_f32_16x16x32_bf16 v[26:29], v[142:145], v[134:137], v[26:29]
	s_waitcnt lgkmcnt(10)
	v_mfma_f32_16x16x32_bf16 v[22:25], v[176:179], v[134:137], v[22:25]
	s_waitcnt lgkmcnt(8)
	v_mfma_f32_16x16x32_bf16 v[18:21], v[180:183], v[134:137], v[18:21]
	s_setprio 0
	ds_read_b64 v[138:139], v210 offset:1088
	ds_read_b64 v[140:141], v210 offset:1120
	ds_read_b64 v[142:143], v212 offset:1344
	ds_read_b64 v[144:145], v212 offset:1376
	ds_read_b64 v[176:177], v213 offset:1600
	ds_read_b64 v[178:179], v213 offset:1632
	ds_read_b64 v[180:181], v214 offset:1856
	ds_read_b64 v[182:183], v214 offset:1888
	v_add_u32_e32 v184, 0x8440, v184
	s_setprio 1
	s_waitcnt lgkmcnt(14)
	v_mfma_f32_16x16x32_bf16 v[14:17], v[194:197], v[134:137], v[14:17]
	s_waitcnt lgkmcnt(12)
	v_mfma_f32_16x16x32_bf16 v[10:13], v[198:201], v[134:137], v[10:13]
	s_waitcnt lgkmcnt(10)
	v_mfma_f32_16x16x32_bf16 v[6:9], v[202:205], v[134:137], v[6:9]
	s_waitcnt lgkmcnt(8)
	v_mfma_f32_16x16x32_bf16 v[2:5], v[206:209], v[134:137], v[2:5]
	s_setprio 0
	ds_read_b64 v[134:135], v215 offset:64
	ds_read_b64 v[136:137], v215 offset:96
	ds_read_b64 v[194:195], v216 offset:320
	ds_read_b64 v[196:197], v216 offset:352
	ds_read_b64 v[198:199], v217 offset:576
	ds_read_b64 v[200:201], v217 offset:608
	ds_read_b64 v[202:203], v226 offset:832
	ds_read_b64 v[204:205], v226 offset:864
	s_setprio 1
	s_waitcnt lgkmcnt(14)
	v_mfma_f32_16x16x32_bf16 v[62:65], v[138:141], v[130:133], v[62:65]
	s_waitcnt lgkmcnt(12)
	v_mfma_f32_16x16x32_bf16 v[58:61], v[142:145], v[130:133], v[58:61]
	s_waitcnt lgkmcnt(10)
	v_mfma_f32_16x16x32_bf16 v[54:57], v[176:179], v[130:133], v[54:57]
	s_waitcnt lgkmcnt(8)
	v_mfma_f32_16x16x32_bf16 v[50:53], v[180:183], v[130:133], v[50:53]
	s_setprio 0
	ds_read_b64 v[138:139], v227 offset:1088
	ds_read_b64 v[140:141], v227 offset:1120
	ds_read_b64 v[142:143], v228 offset:1344
	ds_read_b64 v[144:145], v228 offset:1376
	ds_read_b64 v[176:177], v229 offset:1600
	ds_read_b64 v[178:179], v229 offset:1632
	ds_read_b64 v[180:181], v230 offset:1856
	ds_read_b64 v[182:183], v230 offset:1888
	s_setprio 1
	s_waitcnt lgkmcnt(14)
	v_mfma_f32_16x16x32_bf16 v[46:49], v[134:137], v[130:133], v[46:49]
	s_waitcnt lgkmcnt(12)
	v_mfma_f32_16x16x32_bf16 v[42:45], v[194:197], v[130:133], v[42:45]
	s_waitcnt lgkmcnt(10)
	v_mfma_f32_16x16x32_bf16 v[38:41], v[198:201], v[130:133], v[38:41]
	s_waitcnt lgkmcnt(8)
	v_mfma_f32_16x16x32_bf16 v[34:37], v[202:205], v[130:133], v[34:37]
	s_setprio 0
	ds_read_b64 v[134:135], v231 offset:64
	ds_read_b64 v[136:137], v231 offset:96
	ds_read_b64 v[194:195], v232 offset:320
	ds_read_b64 v[196:197], v232 offset:352
	v_add_u32_e32 v185, 0x7800, v184
	v_add_u32_e32 v184, 0x8000, v184
	ds_read_b64 v[198:199], v185 offset:1536
	ds_read_b64 v[200:201], v185 offset:1568
	ds_read_b64 v[202:203], v184 offset:1792
	ds_read_b64 v[204:205], v184 offset:1824
	s_setprio 1
	s_waitcnt lgkmcnt(14)
	v_mfma_f32_16x16x32_bf16 v[30:33], v[138:141], v[130:133], v[30:33]
	s_waitcnt lgkmcnt(12)
	v_mfma_f32_16x16x32_bf16 v[26:29], v[142:145], v[130:133], v[26:29]
	s_waitcnt lgkmcnt(10)
	v_mfma_f32_16x16x32_bf16 v[22:25], v[176:179], v[130:133], v[22:25]
	s_waitcnt lgkmcnt(8)
	v_mfma_f32_16x16x32_bf16 v[18:21], v[180:183], v[130:133], v[18:21]
	s_setprio 0
	s_setprio 1
	s_waitcnt lgkmcnt(6)
	v_mfma_f32_16x16x32_bf16 v[14:17], v[134:137], v[130:133], v[14:17]
	s_waitcnt lgkmcnt(4)
	v_mfma_f32_16x16x32_bf16 v[10:13], v[194:197], v[130:133], v[10:13]
	s_waitcnt lgkmcnt(2)
	v_mfma_f32_16x16x32_bf16 v[6:9], v[198:201], v[130:133], v[6:9]
	s_waitcnt lgkmcnt(0)
	v_mfma_f32_16x16x32_bf16 v[2:5], v[202:205], v[130:133], v[2:5]
	s_setprio 0
	s_add_i32 s44, s44, 64
	v_lshl_add_u64 v[150:151], v[150:151], 0, s[72:73]
	v_lshl_add_u64 v[152:153], v[152:153], 0, s[72:73]
	v_lshl_add_u64 v[154:155], v[154:155], 0, s[72:73]
	s_cmpk_lg_i32 s44, 0xc0
	v_lshl_add_u64 v[156:157], v[156:157], 0, s[72:73]
	s_mov_b32 s15, s14
	s_cbranch_scc1 .LBB0_601
	s_branch .LBB0_597
